# k32_tightpoll
# baseline (speedup 1.0000x reference)
; #define PH_SYNC(n) run_phase<n>(p, smem); grid.sync();
; __global__ void __launch_bounds__(256, 2) hybrid_fwd(Params p) {
;   __shared__ __attribute__((aligned(16))) char smem[SMEM_BYTES];
;   cg::grid_group grid = cg::this_grid();
;   PH_SYNC(0) PH_SYNC(1) PH_SYNC(2) PH_SYNC(3) PH_SYNC(4) PH_SYNC(5) PH_SYNC(6) PH_SYNC(7)
;   PH_SYNC(8) PH_SYNC(17) PH_SYNC(9) PH_SYNC(10) PH_SYNC(11) PH_SYNC(12) PH_SYNC(13) PH_SYNC(14) PH_SYNC(15)
;   PH_SYNC(16)
.Lmy_gs_poll_1:
	global_load_dword v0, v2, s[10:11] sc1
	s_add_u32 s13, s13, 1
	s_waitcnt vmcnt(0)
	v_cmp_ge_u32_e32 vcc, v0, v1
	s_cmp_lg_u64 vcc, 0
	s_cbranch_scc1 .Lmy_gs_done_1
	s_cmp_lt_u32 s13, 0x40000
	s_cbranch_scc1 .Lmy_gs_poll_1

; #define PH_SYNC(n) run_phase<n>(p, smem); grid.sync();
; __global__ void __launch_bounds__(256, 2) hybrid_fwd(Params p) {
;   __shared__ __attribute__((aligned(16))) char smem[SMEM_BYTES];
;   cg::grid_group grid = cg::this_grid();
;   PH_SYNC(0) PH_SYNC(1) PH_SYNC(2) PH_SYNC(3) PH_SYNC(4) PH_SYNC(5) PH_SYNC(6) PH_SYNC(7)
;   PH_SYNC(8) PH_SYNC(17) PH_SYNC(9) PH_SYNC(10) PH_SYNC(11) PH_SYNC(12) PH_SYNC(13) PH_SYNC(14) PH_SYNC(15)
;   PH_SYNC(16)
.Lmy_gs_poll_3:
	global_load_dword v0, v2, s[8:9] sc1
	s_add_u32 s11, s11, 1
	s_waitcnt vmcnt(0)
	v_cmp_ge_u32_e32 vcc, v0, v1
	s_cmp_lg_u64 vcc, 0
	s_cbranch_scc1 .Lmy_gs_done_3
	s_cmp_lt_u32 s11, 0x40000
	s_cbranch_scc1 .Lmy_gs_poll_3

; #define PH_SYNC(n) run_phase<n>(p, smem); grid.sync();
; __global__ void __launch_bounds__(256, 2) hybrid_fwd(Params p) {
;   __shared__ __attribute__((aligned(16))) char smem[SMEM_BYTES];
;   cg::grid_group grid = cg::this_grid();
;   PH_SYNC(0) PH_SYNC(1) PH_SYNC(2) PH_SYNC(3) PH_SYNC(4) PH_SYNC(5) PH_SYNC(6) PH_SYNC(7)
;   PH_SYNC(8) PH_SYNC(17) PH_SYNC(9) PH_SYNC(10) PH_SYNC(11) PH_SYNC(12) PH_SYNC(13) PH_SYNC(14) PH_SYNC(15)
;   PH_SYNC(16)
.Lmy_gs_poll_5:
	global_load_dword v0, v2, s[12:13] sc1
	s_add_u32 s15, s15, 1
	s_waitcnt vmcnt(0)
	v_cmp_ge_u32_e32 vcc, v0, v1
	s_cmp_lg_u64 vcc, 0
	s_cbranch_scc1 .Lmy_gs_done_5
	s_cmp_lt_u32 s15, 0x40000
	s_cbranch_scc1 .Lmy_gs_poll_5

; #define PH_SYNC(n) run_phase<n>(p, smem); grid.sync();
; __global__ void __launch_bounds__(256, 2) hybrid_fwd(Params p) {
;   __shared__ __attribute__((aligned(16))) char smem[SMEM_BYTES];
;   cg::grid_group grid = cg::this_grid();
;   PH_SYNC(0) PH_SYNC(1) PH_SYNC(2) PH_SYNC(3) PH_SYNC(4) PH_SYNC(5) PH_SYNC(6) PH_SYNC(7)
;   PH_SYNC(8) PH_SYNC(17) PH_SYNC(9) PH_SYNC(10) PH_SYNC(11) PH_SYNC(12) PH_SYNC(13) PH_SYNC(14) PH_SYNC(15)
;   PH_SYNC(16)
.Lsy0_poll:
	global_load_dword v0, v2, s[26:27] sc1
	s_add_u32 s25, s25, 1
	s_waitcnt vmcnt(0)
	v_cmp_ge_u32_e32 vcc, v0, v1
	s_cmp_lg_u64 vcc, 0
	s_cbranch_scc1 .Lsy0_done
	s_cmp_lt_u32 s25, 0x40000
	s_cbranch_scc1 .Lsy0_poll

; #define PH_SYNC(n) run_phase<n>(p, smem); grid.sync();
; __global__ void __launch_bounds__(256, 2) hybrid_fwd(Params p) {
;   __shared__ __attribute__((aligned(16))) char smem[SMEM_BYTES];
;   cg::grid_group grid = cg::this_grid();
;   PH_SYNC(0) PH_SYNC(1) PH_SYNC(2) PH_SYNC(3) PH_SYNC(4) PH_SYNC(5) PH_SYNC(6) PH_SYNC(7)
;   PH_SYNC(8) PH_SYNC(17) PH_SYNC(9) PH_SYNC(10) PH_SYNC(11) PH_SYNC(12) PH_SYNC(13) PH_SYNC(14) PH_SYNC(15)
;   PH_SYNC(16)
.Lmy_gs_poll_9:
	global_load_dword v0, v2, s[14:15] sc1
	s_add_u32 s17, s17, 1
	s_waitcnt vmcnt(0)
	v_cmp_ge_u32_e32 vcc, v0, v1
	s_cmp_lg_u64 vcc, 0
	s_cbranch_scc1 .Lmy_gs_done_9
	s_cmp_lt_u32 s17, 0x40000
	s_cbranch_scc1 .Lmy_gs_poll_9

; #define PH_SYNC(n) run_phase<n>(p, smem); grid.sync();
; __global__ void __launch_bounds__(256, 2) hybrid_fwd(Params p) {
;   __shared__ __attribute__((aligned(16))) char smem[SMEM_BYTES];
;   cg::grid_group grid = cg::this_grid();
;   PH_SYNC(0) PH_SYNC(1) PH_SYNC(2) PH_SYNC(3) PH_SYNC(4) PH_SYNC(5) PH_SYNC(6) PH_SYNC(7)
;   PH_SYNC(8) PH_SYNC(17) PH_SYNC(9) PH_SYNC(10) PH_SYNC(11) PH_SYNC(12) PH_SYNC(13) PH_SYNC(14) PH_SYNC(15)
;   PH_SYNC(16)
.Lmy_gs_poll_16:
	global_load_dword v0, v2, s[6:7] sc1
	s_add_u32 s9, s9, 1
	s_waitcnt vmcnt(0)
	v_cmp_ge_u32_e32 vcc, v0, v1
	s_cmp_lg_u64 vcc, 0
	s_cbranch_scc1 .Lmy_gs_done_16
	s_cmp_lt_u32 s9, 0x40000
	s_cbranch_scc1 .Lmy_gs_poll_16

; #define PH_SYNC(n) run_phase<n>(p, smem); grid.sync();
; __global__ void __launch_bounds__(256, 2) hybrid_fwd(Params p) {
;   __shared__ __attribute__((aligned(16))) char smem[SMEM_BYTES];
;   cg::grid_group grid = cg::this_grid();
;   PH_SYNC(0) PH_SYNC(1) PH_SYNC(2) PH_SYNC(3) PH_SYNC(4) PH_SYNC(5) PH_SYNC(6) PH_SYNC(7)
;   PH_SYNC(8) PH_SYNC(17) PH_SYNC(9) PH_SYNC(10) PH_SYNC(11) PH_SYNC(12) PH_SYNC(13) PH_SYNC(14) PH_SYNC(15)
;   PH_SYNC(16)
.Lmy_gs_poll_17:
	global_load_dword v0, v2, s[0:1] sc1
	s_add_u32 s5, s5, 1
	s_waitcnt vmcnt(0)
	v_cmp_ge_u32_e32 vcc, v0, v1
	s_cmp_lg_u64 vcc, 0
	s_cbranch_scc1 .Lmy_gs_done_17
	s_cmp_lt_u32 s5, 0x40000
	s_cbranch_scc1 .Lmy_gs_poll_17
